# MoBA bias-LUT reads batched (one wait instead of 16) + first-barrier census loads issued together
# baseline (speedup 1.0000x reference)
.LBB0_221:
	v_readlane_b32 s4, v253, 13
	v_readlane_b32 s5, v253, 14
	v_readlane_b32 s3, v253, 10
	s_mov_b64 s[6:7], -1
	s_nop 2
	global_load_dword v1, v0, s[4:5] sc1
	v_readlane_b32 s4, v253, 15
	v_readlane_b32 s5, v253, 16
	s_waitcnt lgkmcnt(0)
	s_nop 3
	global_load_dword v2, v0, s[4:5] sc1
	v_readlane_b32 s4, v253, 17
	v_readlane_b32 s5, v253, 18
	s_nop 4
	global_load_dword v3, v0, s[4:5] sc1
	v_readlane_b32 s4, v253, 19
	v_readlane_b32 s5, v253, 20
	s_nop 4
	global_load_dword v4, v0, s[4:5] sc1
	v_readlane_b32 s4, v253, 21
	v_readlane_b32 s5, v253, 22
	s_nop 4
	global_load_dword v5, v0, s[4:5] sc1
	v_readlane_b32 s4, v253, 23
	v_readlane_b32 s5, v253, 24
	s_nop 4
	global_load_dword v6, v0, s[4:5] sc1
	v_readlane_b32 s4, v253, 25
	v_readlane_b32 s5, v253, 26
	s_nop 4
	global_load_dword v7, v0, s[4:5] sc1
	v_readlane_b32 s4, v253, 27
	v_readlane_b32 s5, v253, 28
	s_nop 4
	global_load_dword v8, v0, s[4:5] sc1
	v_readlane_b32 s4, v253, 29
	v_readlane_b32 s5, v253, 30
	s_nop 4
	global_load_dword v9, v0, s[4:5] sc1
	v_readlane_b32 s4, v253, 31
	v_readlane_b32 s5, v253, 32
	s_nop 4
	global_load_dword v10, v0, s[4:5] sc1
	v_readlane_b32 s4, v253, 33
	v_readlane_b32 s5, v253, 34
	s_nop 4
	global_load_dword v11, v0, s[4:5] sc1
	v_readlane_b32 s4, v253, 35
	v_readlane_b32 s5, v253, 36
	s_nop 4
	global_load_dword v12, v0, s[4:5] sc1
	v_readlane_b32 s4, v253, 37
	v_readlane_b32 s5, v253, 38
	s_nop 4
	global_load_dword v13, v0, s[4:5] sc1
	v_readlane_b32 s4, v253, 39
	v_readlane_b32 s5, v253, 40
	s_nop 4
	global_load_dword v14, v0, s[4:5] sc1
	v_readlane_b32 s4, v253, 41
	v_readlane_b32 s5, v253, 42
	s_nop 4
	global_load_dword v15, v0, s[4:5] sc1
	v_readlane_b32 s4, v253, 43
	v_readlane_b32 s5, v253, 44
	s_nop 4
	global_load_dword v16, v0, s[4:5] sc1
	s_mov_b64 s[4:5], -1
	s_waitcnt vmcnt(0)
	v_add_u32_e32 v17, v2, v1
	v_add_u32_e32 v17, v17, v3
	v_add_u32_e32 v17, v17, v4
	v_add_u32_e32 v17, v17, v5
	v_add_u32_e32 v17, v17, v6
	v_add_u32_e32 v17, v17, v7
	v_add_u32_e32 v17, v17, v8
	v_add_u32_e32 v17, v17, v9
	v_add_u32_e32 v17, v17, v10
	v_add_u32_e32 v17, v17, v11
	v_add_u32_e32 v17, v17, v12
	v_add_u32_e32 v17, v17, v13
	v_add_u32_e32 v17, v17, v14
	v_add_u32_e32 v17, v17, v15
	v_add_u32_e32 v17, v17, v16
	v_cmp_eq_u32_e32 vcc, s3, v17
	s_cbranch_vccnz .LBB0_220
	s_and_b32 s3, s2, 0xff
	s_cmp_eq_u32 s3, 0
	s_mov_b64 s[8:9], -1
	s_sleep 1
	s_cbranch_scc1 .LBB0_225
	s_and_b64 vcc, exec, s[8:9]
	s_cbranch_vccz .LBB0_220
